# SB1 without L2 writeback: pre-norm rows remapped so H stays inside the consuming XCD, w_in^T write-through, count-in is a plain atomic; co-location check with per-XCD-group fallback
# speedup vs baseline: 1.0044x; 1.0044x over previous
.LBB0_34:
	s_andn2_b64 vcc, exec, s[8:9]
	s_cbranch_vccnz .LBB0_15
	s_mul_hi_i32 s0, s26, 0x2aaaaaab
	s_lshr_b32 s8, s0, 31
	s_ashr_i32 s0, s0, 5
	s_add_i32 s0, s0, s8
	s_lshl_b32 s8, s0, 6
	s_mulk_i32 s0, 0xe800
	s_add_i32 s28, s7, s0
	s_ashr_i32 s29, s28, 31
	v_lshl_add_u64 v[80:81], s[28:29], 2, v[26:27]
	v_or_b32_e32 v2, s8, v28
	v_mad_i64_i32 v[52:53], s[30:31], v2, s25, v[80:81]
	v_or_b32_e32 v2, s8, v29
	v_mad_i64_i32 v[56:57], s[30:31], v2, s25, v[80:81]
	v_or_b32_e32 v2, s8, v30
	v_mad_i64_i32 v[60:61], s[30:31], v2, s25, v[80:81]
	v_or_b32_e32 v2, s8, v31
	v_mad_i64_i32 v[64:65], s[30:31], v2, s25, v[80:81]
	v_or_b32_e32 v2, s8, v32
	v_mad_i64_i32 v[68:69], s[30:31], v2, s25, v[80:81]
	v_or_b32_e32 v2, s8, v33
	v_mad_i64_i32 v[72:73], s[30:31], v2, s25, v[80:81]
	global_load_dwordx4 v[52:55], v[52:53], off
	s_nop 0
	global_load_dwordx4 v[56:59], v[56:57], off
	s_nop 0
	global_load_dwordx4 v[60:63], v[60:61], off
	s_nop 0
	global_load_dwordx4 v[64:67], v[64:65], off
	s_nop 0
	global_load_dwordx4 v[68:71], v[68:69], off
	s_nop 0
	global_load_dwordx4 v[72:75], v[72:73], off
	v_or_b32_e32 v2, s8, v34
	v_mad_i64_i32 v[76:77], s[30:31], v2, s25, v[80:81]
	global_load_dwordx4 v[76:79], v[76:77], off
	v_or_b32_e32 v2, s8, v35
	v_mad_i64_i32 v[80:81], s[30:31], v2, s25, v[80:81]
	global_load_dwordx4 v[80:83], v[80:81], off
	v_add_u32_e32 v86, s28, v28
	s_ashr_i32 s9, s8, 31
	v_ashrrev_i32_e32 v87, 31, v86
	v_add_u32_e32 v88, 8, v86
	v_lshl_add_u64 v[84:85], s[8:9], 1, v[14:15]
	v_lshlrev_b64 v[90:91], 11, v[86:87]
	v_ashrrev_i32_e32 v89, 31, v88
	v_lshl_add_u64 v[90:91], v[84:85], 0, v[90:91]
	v_lshlrev_b64 v[88:89], 11, v[88:89]
	v_lshl_add_u64 v[88:89], v[84:85], 0, v[88:89]
	s_waitcnt vmcnt(7)
	ds_write2_b32 v37, v52, v53 offset1:1
	ds_write2_b32 v37, v54, v55 offset0:2 offset1:3
	s_waitcnt vmcnt(6)
	ds_write2_b32 v38, v56, v57 offset1:1
	ds_write2_b32 v39, v58, v59 offset1:1
	s_waitcnt vmcnt(5)
	ds_write2_b32 v40, v60, v61 offset1:1
	ds_write2_b32 v41, v62, v63 offset1:1
	s_waitcnt vmcnt(4)
	ds_write2_b32 v42, v64, v65 offset1:1
	ds_write2_b32 v43, v66, v67 offset1:1
	s_waitcnt vmcnt(3)
	ds_write2_b32 v44, v68, v69 offset1:1
	ds_write2_b32 v45, v70, v71 offset1:1
	s_waitcnt vmcnt(2)
	ds_write2_b32 v46, v72, v73 offset1:1
	ds_write2_b32 v47, v74, v75 offset1:1
	s_waitcnt vmcnt(1)
	ds_write2_b32 v48, v76, v77 offset1:1
	ds_write2_b32 v49, v78, v79 offset1:1
	s_waitcnt vmcnt(0)
	ds_write2_b32 v50, v80, v81 offset1:1
	ds_write2_b32 v51, v82, v83 offset1:1
	s_waitcnt lgkmcnt(0)
	ds_read2_b32 v[54:55], v36 offset0:33 offset1:41
	ds_read2_b32 v[56:57], v36 offset1:8
	ds_read2_b32 v[58:59], v36 offset0:66 offset1:74
	ds_read2_b32 v[60:61], v36 offset0:99 offset1:107
	ds_read2_b32 v[62:63], v36 offset0:132 offset1:140
	ds_read2_b32 v[64:65], v36 offset0:165 offset1:173
	ds_read2_b32 v[66:67], v36 offset0:198 offset1:206
	ds_read2_b32 v[68:69], v36 offset0:231 offset1:239
	ds_read2_b32 v[70:71], v36 offset0:49 offset1:57
	ds_read2_b32 v[72:73], v36 offset0:16 offset1:24
	ds_read2_b32 v[74:75], v36 offset0:82 offset1:90
	ds_read2_b32 v[76:77], v36 offset0:115 offset1:123
	ds_read2_b32 v[78:79], v36 offset0:148 offset1:156
	ds_read2_b32 v[80:81], v36 offset0:181 offset1:189
	ds_read2_b32 v[82:83], v36 offset0:214 offset1:222
	ds_read2_b32 v[92:93], v36 offset0:247 offset1:255
	s_waitcnt lgkmcnt(14)
	v_cvt_pk_bf16_f32 v52, v56, v54
	s_waitcnt lgkmcnt(12)
	v_cvt_pk_bf16_f32 v53, v58, v60
	v_cvt_pk_bf16_f32 v56, v57, v55
	s_waitcnt lgkmcnt(10)
	v_cvt_pk_bf16_f32 v54, v62, v64
	s_waitcnt lgkmcnt(8)
	v_cvt_pk_bf16_f32 v55, v66, v68
	v_cvt_pk_bf16_f32 v57, v59, v61
	v_cvt_pk_bf16_f32 v58, v63, v65
	v_cvt_pk_bf16_f32 v59, v67, v69
	global_store_dwordx4 v[90:91], v[52:55], off sc1
	global_store_dwordx4 v[88:89], v[56:59], off sc1
	s_waitcnt lgkmcnt(6)
	v_cvt_pk_bf16_f32 v60, v72, v70
	v_add_u32_e32 v52, 16, v86
	v_ashrrev_i32_e32 v53, 31, v52
	v_add_u32_e32 v56, 24, v86
	v_lshlrev_b64 v[52:53], 11, v[52:53]
	v_ashrrev_i32_e32 v57, 31, v56
	s_waitcnt lgkmcnt(4)
	v_cvt_pk_bf16_f32 v61, v74, v76
	s_waitcnt lgkmcnt(2)
	v_cvt_pk_bf16_f32 v62, v78, v80
	s_waitcnt lgkmcnt(0)
	v_cvt_pk_bf16_f32 v63, v82, v92
	v_lshl_add_u64 v[52:53], v[84:85], 0, v[52:53]
	v_lshlrev_b64 v[56:57], 11, v[56:57]
	global_store_dwordx4 v[52:53], v[60:63], off sc1
	v_cvt_pk_bf16_f32 v52, v73, v71
	v_cvt_pk_bf16_f32 v53, v75, v77
	v_cvt_pk_bf16_f32 v54, v79, v81
	v_cvt_pk_bf16_f32 v55, v83, v93
	v_lshl_add_u64 v[56:57], v[84:85], 0, v[56:57]
	global_store_dwordx4 v[56:57], v[52:55], off sc1
	s_waitcnt lgkmcnt(0)
	s_branch .LBB0_15

.LBB0_47:
	s_cmp_lg_u32 s100, 0
	s_cbranch_scc1 .Lsb1_wait
	s_and_b32 s4, s2, 7
	s_lshl_b32 s4, s4, 5
	s_lshr_b32 s5, s2, 3
	s_add_i32 s4, s4, s5
	s_lshl_b32 s4, s4, 3
	s_add_i32 s4, s4, s96
	s_cmp_lt_i32 s94, 2
	s_cselect_b64 s[0:1], -1, 0
	s_cmp_gt_i32 s95, 1
	s_cselect_b64 s[8:9], -1, 0
	s_and_b64 s[0:1], s[0:1], s[8:9]
	s_andn2_b64 vcc, exec, s[0:1]
	s_cbranch_vccnz .LBB0_70
	s_mov_b64 s[8:9], exec
	v_readlane_b32 s10, v246, 2
	v_readlane_b32 s11, v246, 3
	s_and_b64 s[10:11], s[8:9], s[10:11]
	s_mov_b64 exec, s[10:11]
	s_cbranch_execz .LBB0_58
	s_min_i32 s5, s3, 0xc0
	s_add_u32 s10, s92, 0x3800
	s_addc_u32 s11, s93, 0
	s_mov_b32 s7, 0x400001
	v_mov_b32_e32 v2, 0
	s_branch .LBB0_51

.LBB0_70:
	s_waitcnt vmcnt(0) lgkmcnt(0)
	s_barrier
	s_mov_b64 s[0:1], exec
	v_readlane_b32 s6, v246, 2
	v_readlane_b32 s7, v246, 3
	s_and_b64 s[6:7], s[0:1], s[6:7]
	s_mov_b64 exec, s[6:7]
	s_cbranch_execz .Lsb1_arr_end
	s_add_u32 s8, s92, 0x57000
	s_addc_u32 s9, s93, 0
	v_mov_b32_e32 v2, 0
	v_mov_b32_e32 v3, 1
	global_atomic_add v2, v3, s[8:9]
	s_add_u32 s14, s92, 0x400
	s_addc_u32 s15, s93, 0
	s_mov_b64 s[16:17], exec
	s_mov_b32 s10, 0x400000

.Lsb1_census_ok:
	v_readlane_b32 s18, v4, s33
	s_nop 3
	v_writelane_b32 v246, s18, 8
.Lsb1_arr_end:
	s_mov_b64 exec, s[0:1]
	s_mov_b32 s100, 1
	s_lshl_b32 s4, s2, 3
	s_add_i32 s4, s96, s4
	s_lshl_b32 s6, s3, 3
	s_and_b32 s5, s97, 0xffffffc0
	v_readlane_b32 s8, v246, 0
	v_readlane_b32 s9, v246, 1
	s_sub_u32 s8, s8, 0xf0
	s_subb_u32 s9, s9, 0
	s_load_dwordx16 s[12:27], s[8:9], 0x80
	s_waitcnt lgkmcnt(0)
	s_branch .LBB0_13

.Lsb1_wpoll:
	global_load_dword v3, v2, s[8:9] sc1
	s_waitcnt vmcnt(0)
	v_cmp_lt_u32_e32 vcc, s11, v3
	s_cbranch_vccnz .Lsb1_w_ok
	s_sleep 1
	s_sub_u32 s10, s10, 1
	s_cmp_lg_u32 s10, 0
	s_cbranch_scc1 .Lsb1_wpoll
	s_branch .Lsb1_w_end
.Lsb1_w_ok:
	s_and_b32 s14, s2, 7
	s_lshl_b32 s14, s14, 2
	s_add_u32 s14, s14, 0x54200
	s_add_u32 s14, s92, s14
	s_addc_u32 s15, s93, 0
	global_load_dword v3, v2, s[14:15] sc1
	global_load_dword v4, v2, s[14:15] offset:32 sc1
	s_waitcnt vmcnt(0)
	v_add_u32_e32 v5, -1, v3
	v_and_b32_e32 v5, v5, v3
	v_xor_b32_e32 v4, v4, v3
	v_or_b32_e32 v5, v5, v4
	v_cmp_ne_u32_e32 vcc, 0, v5
	s_cbranch_vccz .Lsb1_w_end
	buffer_wbl2 sc1
	s_waitcnt vmcnt(0)
	s_and_b32 s14, s2, 7
	s_lshl_b32 s14, s14, 8
	s_add_u32 s14, s14, 0x57200
	s_add_u32 s14, s92, s14
	s_addc_u32 s15, s93, 0
	v_mov_b32_e32 v3, 1
	global_atomic_add v2, v3, s[14:15]
	s_movk_i32 s11, 31
.Lsb1_hpoll:
	global_load_dword v3, v2, s[14:15] sc1
	s_waitcnt vmcnt(0)
	v_cmp_lt_u32_e32 vcc, s11, v3
	s_cbranch_vccnz .Lsb1_hdone
	s_sleep 1
	s_sub_u32 s10, s10, 1
	s_cmp_lg_u32 s10, 0
	s_cbranch_scc1 .Lsb1_hpoll
.Lsb1_hdone:
	buffer_inv sc1
	s_waitcnt vmcnt(0)
.Lsb1_w_end:
	s_mov_b64 exec, s[0:1]
	s_barrier
	s_mov_b64 s[4:5], -1
